# FFN-in GEMM epilogue (SwiGLU) regenerated: per 8 outputs, packed f32 scale / +1 / products (v_pk_mul/add_f32), exp and rcp batched; same operation order per element
# baseline (speedup 1.0000x reference)
.LBB0_270:
	s_mov_b32 s100, 0xbfb8aa3b
	s_mov_b32 s101, 0xbfb8aa3b
	s_waitcnt lgkmcnt(0)
	v_pk_mul_f32 v[148:149], v[132:133], s[100:101]
	v_pk_mul_f32 v[150:151], v[134:135], s[100:101]
	v_pk_mul_f32 v[152:153], v[128:129], s[100:101]
	v_pk_mul_f32 v[154:155], v[130:131], s[100:101]
	v_exp_f32_e32 v148, v148
	v_exp_f32_e32 v149, v149
	v_exp_f32_e32 v150, v150
	v_exp_f32_e32 v151, v151
	v_exp_f32_e32 v152, v152
	v_exp_f32_e32 v153, v153
	v_exp_f32_e32 v154, v154
	v_exp_f32_e32 v155, v155
	v_pk_add_f32 v[148:149], v[148:149], 1.0 op_sel_hi:[1,0]
	v_pk_add_f32 v[150:151], v[150:151], 1.0 op_sel_hi:[1,0]
	v_pk_add_f32 v[152:153], v[152:153], 1.0 op_sel_hi:[1,0]
	v_pk_add_f32 v[154:155], v[154:155], 1.0 op_sel_hi:[1,0]
	v_rcp_f32_e32 v148, v148
	v_rcp_f32_e32 v149, v149
	v_rcp_f32_e32 v150, v150
	v_rcp_f32_e32 v151, v151
	v_rcp_f32_e32 v152, v152
	v_rcp_f32_e32 v153, v153
	v_rcp_f32_e32 v154, v154
	v_rcp_f32_e32 v155, v155
	v_pk_mul_f32 v[148:149], v[132:133], v[148:149]
	v_pk_mul_f32 v[150:151], v[134:135], v[150:151]
	v_pk_mul_f32 v[152:153], v[128:129], v[152:153]
	v_pk_mul_f32 v[154:155], v[130:131], v[154:155]
	v_pk_mul_f32 v[148:149], v[148:149], v[124:125]
	v_pk_mul_f32 v[150:151], v[150:151], v[126:127]
	v_pk_mul_f32 v[152:153], v[152:153], v[120:121]
	v_pk_mul_f32 v[154:155], v[154:155], v[122:123]
	v_cvt_pk_bf16_f32 v156, v148, v149
	v_cvt_pk_bf16_f32 v157, v150, v151
	v_cvt_pk_bf16_f32 v158, v152, v153
	v_cvt_pk_bf16_f32 v159, v154, v155
	s_lshl_b32 s12, s42, 8
	s_cmp_gt_i32 s72, 0
	s_cselect_b32 s13, 0x80, 0
	v_pk_mul_f32 v[148:149], v[116:117], s[100:101]
	v_pk_mul_f32 v[150:151], v[118:119], s[100:101]
	v_pk_mul_f32 v[152:153], v[112:113], s[100:101]
	v_pk_mul_f32 v[154:155], v[114:115], s[100:101]
	v_exp_f32_e32 v148, v148
	v_exp_f32_e32 v149, v149
	v_exp_f32_e32 v150, v150
	v_exp_f32_e32 v151, v151
	v_exp_f32_e32 v152, v152
	v_exp_f32_e32 v153, v153
	v_exp_f32_e32 v154, v154
	v_exp_f32_e32 v155, v155
	v_pk_add_f32 v[148:149], v[148:149], 1.0 op_sel_hi:[1,0]
	v_pk_add_f32 v[150:151], v[150:151], 1.0 op_sel_hi:[1,0]
	v_pk_add_f32 v[152:153], v[152:153], 1.0 op_sel_hi:[1,0]
	v_pk_add_f32 v[154:155], v[154:155], 1.0 op_sel_hi:[1,0]
	v_rcp_f32_e32 v148, v148
	v_rcp_f32_e32 v149, v149
	v_rcp_f32_e32 v150, v150
	v_rcp_f32_e32 v151, v151
	v_rcp_f32_e32 v152, v152
	v_rcp_f32_e32 v153, v153
	v_rcp_f32_e32 v154, v154
	v_rcp_f32_e32 v155, v155
	v_pk_mul_f32 v[148:149], v[116:117], v[148:149]
	v_pk_mul_f32 v[150:151], v[118:119], v[150:151]
	v_pk_mul_f32 v[152:153], v[112:113], v[152:153]
	v_pk_mul_f32 v[154:155], v[114:115], v[154:155]
	v_pk_mul_f32 v[148:149], v[148:149], v[108:109]
	v_pk_mul_f32 v[150:151], v[150:151], v[110:111]
	v_pk_mul_f32 v[152:153], v[152:153], v[104:105]
	v_pk_mul_f32 v[154:155], v[154:155], v[106:107]
	v_cvt_pk_bf16_f32 v160, v148, v149
	v_cvt_pk_bf16_f32 v161, v150, v151
	v_cvt_pk_bf16_f32 v162, v152, v153
	v_cvt_pk_bf16_f32 v163, v154, v155
	v_lshl_or_b32 v140, s44, 7, v7
	s_or_b32 s12, s12, s13
	v_add_u32_e32 v138, s12, v1
	v_ashrrev_i32_e32 v141, 31, v140
	v_mov_b64_e32 v[136:137], s[10:11]
	s_movk_i32 s14, 0x2c00
	v_mad_i64_i32 v[144:145], s[12:13], v138, s14, v[136:137]
	v_lshlrev_b64 v[120:121], 1, v[140:141]
	v_lshl_add_u64 v[132:133], v[144:145], 0, v[120:121]
	global_store_dwordx4 v[132:133], v[156:159], off
	s_cmp_gt_i32 s72, -1
	s_nop 0
	v_or_b32_e32 v124, 16, v138
	v_mad_i64_i32 v[124:125], s[12:13], v124, s14, v[136:137]
	v_lshl_add_u64 v[116:117], v[124:125], 0, v[120:121]
	v_pk_mul_f32 v[148:149], v[100:101], s[100:101]
	v_pk_mul_f32 v[150:151], v[102:103], s[100:101]
	v_pk_mul_f32 v[152:153], v[96:97], s[100:101]
	v_pk_mul_f32 v[154:155], v[98:99], s[100:101]
	v_exp_f32_e32 v148, v148
	v_exp_f32_e32 v149, v149
	v_exp_f32_e32 v150, v150
	v_exp_f32_e32 v151, v151
	v_exp_f32_e32 v152, v152
	v_exp_f32_e32 v153, v153
	v_exp_f32_e32 v154, v154
	v_exp_f32_e32 v155, v155
	v_pk_add_f32 v[148:149], v[148:149], 1.0 op_sel_hi:[1,0]
	v_pk_add_f32 v[150:151], v[150:151], 1.0 op_sel_hi:[1,0]
	v_pk_add_f32 v[152:153], v[152:153], 1.0 op_sel_hi:[1,0]
	v_pk_add_f32 v[154:155], v[154:155], 1.0 op_sel_hi:[1,0]
	v_rcp_f32_e32 v148, v148
	v_rcp_f32_e32 v149, v149
	v_rcp_f32_e32 v150, v150
	v_rcp_f32_e32 v151, v151
	v_rcp_f32_e32 v152, v152
	v_rcp_f32_e32 v153, v153
	v_rcp_f32_e32 v154, v154
	v_rcp_f32_e32 v155, v155
	v_pk_mul_f32 v[148:149], v[100:101], v[148:149]
	v_pk_mul_f32 v[150:151], v[102:103], v[150:151]
	v_pk_mul_f32 v[152:153], v[96:97], v[152:153]
	v_pk_mul_f32 v[154:155], v[98:99], v[154:155]
	v_pk_mul_f32 v[148:149], v[148:149], v[92:93]
	v_pk_mul_f32 v[150:151], v[150:151], v[94:95]
	v_pk_mul_f32 v[152:153], v[152:153], v[88:89]
	v_pk_mul_f32 v[154:155], v[154:155], v[90:91]
	v_cvt_pk_bf16_f32 v156, v148, v149
	v_cvt_pk_bf16_f32 v157, v150, v151
	v_cvt_pk_bf16_f32 v158, v152, v153
	v_cvt_pk_bf16_f32 v159, v154, v155
	global_store_dwordx4 v[116:117], v[160:163], off
	s_nop 1
	v_or_b32_e32 v106, 32, v138
	v_mad_i64_i32 v[106:107], s[12:13], v106, s14, v[136:137]
	v_lshl_add_u64 v[100:101], v[106:107], 0, v[120:121]
	v_pk_mul_f32 v[148:149], v[84:85], s[100:101]
	v_pk_mul_f32 v[150:151], v[86:87], s[100:101]
	v_pk_mul_f32 v[152:153], v[80:81], s[100:101]
	v_pk_mul_f32 v[154:155], v[82:83], s[100:101]
	v_exp_f32_e32 v148, v148
	v_exp_f32_e32 v149, v149
	v_exp_f32_e32 v150, v150
	v_exp_f32_e32 v151, v151
	v_exp_f32_e32 v152, v152
	v_exp_f32_e32 v153, v153
	v_exp_f32_e32 v154, v154
	v_exp_f32_e32 v155, v155
	v_pk_add_f32 v[148:149], v[148:149], 1.0 op_sel_hi:[1,0]
	v_pk_add_f32 v[150:151], v[150:151], 1.0 op_sel_hi:[1,0]
	v_pk_add_f32 v[152:153], v[152:153], 1.0 op_sel_hi:[1,0]
	v_pk_add_f32 v[154:155], v[154:155], 1.0 op_sel_hi:[1,0]
	v_rcp_f32_e32 v148, v148
	v_rcp_f32_e32 v149, v149
	v_rcp_f32_e32 v150, v150
	v_rcp_f32_e32 v151, v151
	v_rcp_f32_e32 v152, v152
	v_rcp_f32_e32 v153, v153
	v_rcp_f32_e32 v154, v154
	v_rcp_f32_e32 v155, v155
	v_pk_mul_f32 v[148:149], v[84:85], v[148:149]
	v_pk_mul_f32 v[150:151], v[86:87], v[150:151]
	v_pk_mul_f32 v[152:153], v[80:81], v[152:153]
	v_pk_mul_f32 v[154:155], v[82:83], v[154:155]
	v_pk_mul_f32 v[148:149], v[148:149], v[76:77]
	v_pk_mul_f32 v[150:151], v[150:151], v[78:79]
	v_pk_mul_f32 v[152:153], v[152:153], v[72:73]
	v_pk_mul_f32 v[154:155], v[154:155], v[74:75]
	v_cvt_pk_bf16_f32 v160, v148, v149
	v_cvt_pk_bf16_f32 v161, v150, v151
	v_cvt_pk_bf16_f32 v162, v152, v153
	v_cvt_pk_bf16_f32 v163, v154, v155
	global_store_dwordx4 v[100:101], v[156:159], off
	s_nop 1
	v_or_b32_e32 v90, 48, v138
	v_mad_i64_i32 v[90:91], s[12:13], v90, s14, v[136:137]
	v_lshl_add_u64 v[84:85], v[90:91], 0, v[120:121]
	global_store_dwordx4 v[84:85], v[160:163], off
	s_cbranch_scc0 .LBB0_272
	s_andn2_b64 vcc, exec, s[36:37]
	s_mov_b64 s[12:13], -1
	s_cbranch_vccnz .LBB0_244
	s_branch .LBB0_273
.LBB0_272:
	s_nop 0
	v_pk_mul_f32 v[148:149], v[68:69], s[100:101]
	v_pk_mul_f32 v[150:151], v[70:71], s[100:101]
	v_pk_mul_f32 v[152:153], v[64:65], s[100:101]
	v_pk_mul_f32 v[154:155], v[66:67], s[100:101]
	v_exp_f32_e32 v148, v148
	v_exp_f32_e32 v149, v149
	v_exp_f32_e32 v150, v150
	v_exp_f32_e32 v151, v151
	v_exp_f32_e32 v152, v152
	v_exp_f32_e32 v153, v153
	v_exp_f32_e32 v154, v154
	v_exp_f32_e32 v155, v155
	v_pk_add_f32 v[148:149], v[148:149], 1.0 op_sel_hi:[1,0]
	v_pk_add_f32 v[150:151], v[150:151], 1.0 op_sel_hi:[1,0]
	v_pk_add_f32 v[152:153], v[152:153], 1.0 op_sel_hi:[1,0]
	v_pk_add_f32 v[154:155], v[154:155], 1.0 op_sel_hi:[1,0]
	v_rcp_f32_e32 v148, v148
	v_rcp_f32_e32 v149, v149
	v_rcp_f32_e32 v150, v150
	v_rcp_f32_e32 v151, v151
	v_rcp_f32_e32 v152, v152
	v_rcp_f32_e32 v153, v153
	v_rcp_f32_e32 v154, v154
	v_rcp_f32_e32 v155, v155
	v_pk_mul_f32 v[148:149], v[68:69], v[148:149]
	v_pk_mul_f32 v[150:151], v[70:71], v[150:151]
	v_pk_mul_f32 v[152:153], v[64:65], v[152:153]
	v_pk_mul_f32 v[154:155], v[66:67], v[154:155]
	v_pk_mul_f32 v[148:149], v[148:149], v[60:61]
	v_pk_mul_f32 v[150:151], v[150:151], v[62:63]
	v_pk_mul_f32 v[152:153], v[152:153], v[56:57]
	v_pk_mul_f32 v[154:155], v[154:155], v[58:59]
	v_cvt_pk_bf16_f32 v156, v148, v149
	v_cvt_pk_bf16_f32 v157, v150, v151
	v_cvt_pk_bf16_f32 v158, v152, v153
	v_cvt_pk_bf16_f32 v159, v154, v155
	v_add_u32_e32 v76, 0x80, v138
	v_mov_b64_e32 v[72:73], s[10:11]
	v_mad_i64_i32 v[76:77], s[12:13], v76, s14, v[72:73]
	v_lshl_add_u64 v[68:69], v[76:77], 0, v[120:121]
	v_pk_mul_f32 v[148:149], v[52:53], s[100:101]
	v_pk_mul_f32 v[150:151], v[54:55], s[100:101]
	v_pk_mul_f32 v[152:153], v[48:49], s[100:101]
	v_pk_mul_f32 v[154:155], v[50:51], s[100:101]
	v_exp_f32_e32 v148, v148
	v_exp_f32_e32 v149, v149
	v_exp_f32_e32 v150, v150
	v_exp_f32_e32 v151, v151
	v_exp_f32_e32 v152, v152
	v_exp_f32_e32 v153, v153
	v_exp_f32_e32 v154, v154
	v_exp_f32_e32 v155, v155
	v_pk_add_f32 v[148:149], v[148:149], 1.0 op_sel_hi:[1,0]
	v_pk_add_f32 v[150:151], v[150:151], 1.0 op_sel_hi:[1,0]
	v_pk_add_f32 v[152:153], v[152:153], 1.0 op_sel_hi:[1,0]
	v_pk_add_f32 v[154:155], v[154:155], 1.0 op_sel_hi:[1,0]
	v_rcp_f32_e32 v148, v148
	v_rcp_f32_e32 v149, v149
	v_rcp_f32_e32 v150, v150
	v_rcp_f32_e32 v151, v151
	v_rcp_f32_e32 v152, v152
	v_rcp_f32_e32 v153, v153
	v_rcp_f32_e32 v154, v154
	v_rcp_f32_e32 v155, v155
	v_pk_mul_f32 v[148:149], v[52:53], v[148:149]
	v_pk_mul_f32 v[150:151], v[54:55], v[150:151]
	v_pk_mul_f32 v[152:153], v[48:49], v[152:153]
	v_pk_mul_f32 v[154:155], v[50:51], v[154:155]
	v_pk_mul_f32 v[148:149], v[148:149], v[44:45]
	v_pk_mul_f32 v[150:151], v[150:151], v[46:47]
	v_pk_mul_f32 v[152:153], v[152:153], v[40:41]
	v_pk_mul_f32 v[154:155], v[154:155], v[42:43]
	v_cvt_pk_bf16_f32 v160, v148, v149
	v_cvt_pk_bf16_f32 v161, v150, v151
	v_cvt_pk_bf16_f32 v162, v152, v153
	v_cvt_pk_bf16_f32 v163, v154, v155
	global_store_dwordx4 v[68:69], v[156:159], off
	s_nop 1
	v_add_u32_e32 v58, 0x90, v138
	v_mad_i64_i32 v[58:59], s[12:13], v58, s14, v[72:73]
	v_lshl_add_u64 v[52:53], v[58:59], 0, v[120:121]
	v_pk_mul_f32 v[148:149], v[36:37], s[100:101]
	v_pk_mul_f32 v[150:151], v[38:39], s[100:101]
	v_pk_mul_f32 v[152:153], v[32:33], s[100:101]
	v_pk_mul_f32 v[154:155], v[34:35], s[100:101]
	v_exp_f32_e32 v148, v148
	v_exp_f32_e32 v149, v149
	v_exp_f32_e32 v150, v150
	v_exp_f32_e32 v151, v151
	v_exp_f32_e32 v152, v152
	v_exp_f32_e32 v153, v153
	v_exp_f32_e32 v154, v154
	v_exp_f32_e32 v155, v155
	v_pk_add_f32 v[148:149], v[148:149], 1.0 op_sel_hi:[1,0]
	v_pk_add_f32 v[150:151], v[150:151], 1.0 op_sel_hi:[1,0]
	v_pk_add_f32 v[152:153], v[152:153], 1.0 op_sel_hi:[1,0]
	v_pk_add_f32 v[154:155], v[154:155], 1.0 op_sel_hi:[1,0]
	v_rcp_f32_e32 v148, v148
	v_rcp_f32_e32 v149, v149
	v_rcp_f32_e32 v150, v150
	v_rcp_f32_e32 v151, v151
	v_rcp_f32_e32 v152, v152
	v_rcp_f32_e32 v153, v153
	v_rcp_f32_e32 v154, v154
	v_rcp_f32_e32 v155, v155
	v_pk_mul_f32 v[148:149], v[36:37], v[148:149]
	v_pk_mul_f32 v[150:151], v[38:39], v[150:151]
	v_pk_mul_f32 v[152:153], v[32:33], v[152:153]
	v_pk_mul_f32 v[154:155], v[34:35], v[154:155]
	v_pk_mul_f32 v[148:149], v[148:149], v[28:29]
	v_pk_mul_f32 v[150:151], v[150:151], v[30:31]
	v_pk_mul_f32 v[152:153], v[152:153], v[24:25]
	v_pk_mul_f32 v[154:155], v[154:155], v[26:27]
	v_cvt_pk_bf16_f32 v156, v148, v149
	v_cvt_pk_bf16_f32 v157, v150, v151
	v_cvt_pk_bf16_f32 v158, v152, v153
	v_cvt_pk_bf16_f32 v159, v154, v155
	global_store_dwordx4 v[52:53], v[160:163], off
	s_nop 1
	v_add_u32_e32 v42, 0xa0, v138
	v_mad_i64_i32 v[42:43], s[12:13], v42, s14, v[72:73]
	v_lshl_add_u64 v[36:37], v[42:43], 0, v[120:121]
	v_pk_mul_f32 v[148:149], v[20:21], s[100:101]
	v_pk_mul_f32 v[150:151], v[22:23], s[100:101]
	v_pk_mul_f32 v[152:153], v[16:17], s[100:101]
	v_pk_mul_f32 v[154:155], v[18:19], s[100:101]
	v_exp_f32_e32 v148, v148
	v_exp_f32_e32 v149, v149
	v_exp_f32_e32 v150, v150
	v_exp_f32_e32 v151, v151
	v_exp_f32_e32 v152, v152
	v_exp_f32_e32 v153, v153
	v_exp_f32_e32 v154, v154
	v_exp_f32_e32 v155, v155
	v_pk_add_f32 v[148:149], v[148:149], 1.0 op_sel_hi:[1,0]
	v_pk_add_f32 v[150:151], v[150:151], 1.0 op_sel_hi:[1,0]
	v_pk_add_f32 v[152:153], v[152:153], 1.0 op_sel_hi:[1,0]
	v_pk_add_f32 v[154:155], v[154:155], 1.0 op_sel_hi:[1,0]
	v_rcp_f32_e32 v148, v148
	v_rcp_f32_e32 v149, v149
	v_rcp_f32_e32 v150, v150
	v_rcp_f32_e32 v151, v151
	v_rcp_f32_e32 v152, v152
	v_rcp_f32_e32 v153, v153
	v_rcp_f32_e32 v154, v154
	v_rcp_f32_e32 v155, v155
	v_pk_mul_f32 v[148:149], v[20:21], v[148:149]
	v_pk_mul_f32 v[150:151], v[22:23], v[150:151]
	v_pk_mul_f32 v[152:153], v[16:17], v[152:153]
	v_pk_mul_f32 v[154:155], v[18:19], v[154:155]
	v_pk_mul_f32 v[148:149], v[148:149], v[12:13]
	v_pk_mul_f32 v[150:151], v[150:151], v[14:15]
	v_pk_mul_f32 v[152:153], v[152:153], v[8:9]
	v_pk_mul_f32 v[154:155], v[154:155], v[10:11]
	v_cvt_pk_bf16_f32 v160, v148, v149
	v_cvt_pk_bf16_f32 v161, v150, v151
	v_cvt_pk_bf16_f32 v162, v152, v153
	v_cvt_pk_bf16_f32 v163, v154, v155
	global_store_dwordx4 v[36:37], v[156:159], off
	s_nop 1
	v_add_u32_e32 v26, 0xb0, v138
	v_mad_i64_i32 v[26:27], s[12:13], v26, s14, v[72:73]
	v_lshl_add_u64 v[20:21], v[26:27], 0, v[120:121]
	global_store_dwordx4 v[20:21], v[160:163], off
	s_andn2_b64 vcc, exec, s[36:37]
	s_mov_b64 s[12:13], -1
	s_cbranch_vccnz .LBB0_244

	.amdhsa_kernel _Z9trunk_fwd4Args
		.amdhsa_group_segment_fixed_size 0
		.amdhsa_private_segment_fixed_size 0
		.amdhsa_kernarg_size 576
		.amdhsa_user_sgpr_count 2
		.amdhsa_user_sgpr_dispatch_ptr 0
		.amdhsa_user_sgpr_queue_ptr 0
		.amdhsa_user_sgpr_kernarg_segment_ptr 1
		.amdhsa_user_sgpr_dispatch_id 0
		.amdhsa_user_sgpr_kernarg_preload_length 0
		.amdhsa_user_sgpr_kernarg_preload_offset 0
		.amdhsa_user_sgpr_private_segment_size 0
		.amdhsa_uses_dynamic_stack 0
		.amdhsa_enable_private_segment 0
		.amdhsa_system_sgpr_workgroup_id_x 1
		.amdhsa_system_sgpr_workgroup_id_y 0
		.amdhsa_system_sgpr_workgroup_id_z 0
		.amdhsa_system_sgpr_workgroup_info 0
		.amdhsa_system_vgpr_workitem_id 0
		.amdhsa_next_free_vgpr 256
		.amdhsa_next_free_sgpr 102
		.amdhsa_accum_offset 256
		.amdhsa_reserve_vcc 1
		.amdhsa_float_round_mode_32 0
		.amdhsa_float_round_mode_16_64 0
		.amdhsa_float_denorm_mode_32 3
		.amdhsa_float_denorm_mode_16_64 3
		.amdhsa_dx10_clamp 1
		.amdhsa_ieee_mode 1
		.amdhsa_fp16_overflow 0
		.amdhsa_tg_split 0
		.amdhsa_exception_fp_ieee_invalid_op 0
		.amdhsa_exception_fp_denorm_src 0
		.amdhsa_exception_fp_ieee_div_zero 0
		.amdhsa_exception_fp_ieee_overflow 0
		.amdhsa_exception_fp_ieee_underflow 0
		.amdhsa_exception_fp_ieee_inexact 0
		.amdhsa_exception_int_div_zero 0
	.end_amdhsa_kernel

amdhsa.kernels:
  - .agpr_count:     0
    .args:
      - .offset:         0
        .size:           320
        .value_kind:     by_value
      - .offset:         320
        .size:           4
        .value_kind:     hidden_block_count_x
      - .offset:         324
        .size:           4
        .value_kind:     hidden_block_count_y
      - .offset:         328
        .size:           4
        .value_kind:     hidden_block_count_z
      - .offset:         332
        .size:           2
        .value_kind:     hidden_group_size_x
      - .offset:         334
        .size:           2
        .value_kind:     hidden_group_size_y
      - .offset:         336
        .size:           2
        .value_kind:     hidden_group_size_z
      - .offset:         338
        .size:           2
        .value_kind:     hidden_remainder_x
      - .offset:         340
        .size:           2
        .value_kind:     hidden_remainder_y
      - .offset:         342
        .size:           2
        .value_kind:     hidden_remainder_z
      - .offset:         360
        .size:           8
        .value_kind:     hidden_global_offset_x
      - .offset:         368
        .size:           8
        .value_kind:     hidden_global_offset_y
      - .offset:         376
        .size:           8
        .value_kind:     hidden_global_offset_z
      - .offset:         384
        .size:           2
        .value_kind:     hidden_grid_dims
      - .offset:         440
        .size:           4
        .value_kind:     hidden_dynamic_lds_size
    .group_segment_fixed_size: 0
    .kernarg_segment_align: 8
    .kernarg_segment_size: 576
    .language:       OpenCL C
    .language_version:
      - 2
      - 0
    .max_flat_workgroup_size: 512
    .name:           _Z9trunk_fwd4Args
    .private_segment_fixed_size: 0
    .sgpr_count:     108
    .sgpr_spill_count: 394
    .symbol:         _Z9trunk_fwd4Args.kd
    .uniform_work_group_size: 1
    .uses_dynamic_stack: false
    .vgpr_count:     256
    .vgpr_spill_count: 0
    .wavefront_size: 64
